# main G1 static tile order rotates the N tile by the XCD-local group index so every workgroup meets each of the 12 epilogue types once (was 3 types x4)
# speedup vs baseline: 1.0074x; 1.0074x over previous
.LBB0_54:
	s_add_i32 s88, s88, 1
	s_mul_i32 s6, s88, s79
	s_mul_hi_u32 s7, s88, s78
	s_add_i32 s7, s7, s6
	s_mul_i32 s6, s88, s78
	s_add_u32 s6, s6, s82
	s_addc_u32 s7, s7, s81
	v_cmp_gt_i64_e32 vcc, s[6:7], v[192:193]
	s_mov_b32 s70, s82
	v_cmp_lt_i64_e64 s[42:43], s[6:7], v[190:191]
	s_cbranch_vccnz .LBB0_56
	s_ashr_i32 s7, s6, 31
	s_lshr_b32 s7, s7, 29
	s_add_i32 s7, s6, s7
	s_ashr_i32 s9, s7, 3
	s_and_b32 s7, s7, -8
	s_sub_i32 s6, s6, s7
	s_cmp_lt_i32 s6, 0
	s_movk_i32 s7, 0x181
	s_cselect_b32 s7, s7, 0x180
	s_mul_i32 s6, s6, s7
	s_add_i32 s6, s6, s9
	s_mul_hi_i32 s7, s6, 0x2aaaaaab
	s_lshr_b32 s9, s7, 31
	s_ashr_i32 s7, s7, 4
	s_add_i32 s7, s7, s9
	s_lshl_b32 s9, s7, 3
	s_sub_i32 s11, 0x100, s9
	s_min_i32 s11, s11, 8
	s_abs_i32 s12, s11
	v_cvt_f32_u32_e32 v0, s12
	s_sub_i32 s14, 0, s12
	s_mulk_i32 s7, 0x60
	s_sub_i32 s6, s6, s7
	v_rcp_iflag_f32_e32 v0, v0
	s_abs_i32 s7, s6
	s_xor_b32 s13, s6, s11
	s_ashr_i32 s13, s13, 31
	v_mul_f32_e32 v0, 0x4f7ffffe, v0
	v_cvt_u32_f32_e32 v0, v0
	s_nop 0
	v_readfirstlane_b32 s15, v0
	s_mul_i32 s14, s14, s15
	s_mul_hi_u32 s14, s15, s14
	s_add_i32 s15, s15, s14
	s_mul_hi_u32 s14, s7, s15
	s_mul_i32 s15, s14, s12
	s_sub_i32 s7, s7, s15
	s_add_i32 s16, s14, 1
	s_sub_i32 s15, s7, s12
	s_cmp_ge_u32 s7, s12
	s_cselect_b32 s14, s16, s14
	s_cselect_b32 s7, s15, s7
	s_add_i32 s15, s14, 1
	s_cmp_ge_u32 s7, s12
	s_cselect_b32 s7, s15, s14
	s_xor_b32 s7, s7, s13
	s_sub_i32 s92, s7, s13
	s_mul_i32 s7, s92, s11
	s_sub_i32 s6, s6, s7
	s_add_i32 s94, s9, s6
	s_lshr_b32 s6, s9, 3
	s_and_b32 s6, s6, 3
	s_add_i32 s92, s92, s6
	s_add_i32 s6, s92, -12
	s_cmp_gt_i32 s92, 11
	s_cselect_b32 s92, s6, s92
